# static s_setprio 1 for waves 4-7 during the ret_state+attention and ret_out phases (strategy 4)
# speedup vs baseline: 1.0114x; 1.0015x over previous
; #define PHASED(flag, ph, ...) if ((ph) >= lo && (ph) < hi) { __VA_ARGS__; if (DUPMASK & (flag)) { xcd_barrier(xb, wv); __VA_ARGS__; } if ((ph) + 1 < hi) xcd_barrier(xb, wv); }
; DEVI void ph_ret_state(const int wv, const Params& p, int l, unsigned char* lds_raw) {
;     ...
;     for (int it = blockIdx.x; it < 256; it += gridDim.x) {
;         const int b = it >> 4, h = (it >> 2) & 3, dir = (it >> 1) & 1, half = it & 1;
;         const float e_ = p.in[9][(l * 2 + dir) * 4 + h];
;         const float lg2 = log1pf(-exp2f(-e_)) * 1.4426950408889634f;
;         const float gC = exp2f(128.0f * lg2);
;         f32x4 R[2]; R[0] = (f32x4){0.f, 0.f, 0.f, 0.f}; R[1] = R[0];
;         const int j0 = tid >> 3, g80 = tid & 7;
;         const float wj0 = exp2f((float)(dir == 0 ? 127 - j0 : j0) * lg2), wj1 = exp2f((float)(dir == 0 ? 63 - j0 : j0 + 64) * lg2);
;         u32x4 kwr[2], vwr[2];
; __global__ void __launch_bounds__(NTHREADS) mega(Params p) {
;     ...
;         PHASED(4, b + 3, ph_ret_state(wv, p, l, lds_raw); ph_attn(wv, p, l, lds_raw))
.LBB0_538:
	s_andn2_b64 vcc, exec, s[0:1]
	s_cbranch_vccnz .LBB0_723
	s_cmp_ge_u32 s94, 4
	s_cbranch_scc0 .Lprio_skip_0
	s_setprio 1
.Lprio_skip_0:
	v_readlane_b32 s0, v252, 25
	v_readlane_b32 s1, v252, 26
	s_andn2_b64 vcc, exec, s[0:1]
	s_mov_b32 s39, 0xc2fc0000
	s_waitcnt lgkmcnt(0)
	v_mbcnt_lo_u32_b32 v2, -1, 0
	v_mbcnt_hi_u32_b32 v2, -1, v2
	s_cbranch_vccnz .LBB0_547
	v_readlane_b32 s0, v250, 8
	v_and_b32_e32 v19, 15, v2
	v_bfe_u32 v4, v2, 2, 2
	v_add_u32_e32 v0, s0, v2
	v_readlane_b32 s0, v253, 31
	v_ashrrev_i32_e32 v25, 3, v0
	v_and_b32_e32 v0, 7, v2
	s_lshl_b32 s28, s0, 3
	v_lshlrev_b32_e32 v18, 3, v0
	v_lshlrev_b32_e32 v45, 4, v0
	v_lshrrev_b32_e32 v0, 1, v2
	v_readlane_b32 s0, v252, 30
	v_and_b32_e32 v0, 24, v0
	v_readlane_b32 s1, v252, 31
	v_lshlrev_b32_e32 v2, 3, v2
	v_and_b32_e32 v47, 24, v2
	v_lshl_add_u64 v[20:21], s[0:1], 0, v[0:1]
	v_readlane_b32 s0, v252, 32
	s_movk_i32 s1, 0x90
	v_or_b32_e32 v0, v0, v4
	v_add_u32_e32 v2, s0, v47
	v_readlane_b32 s0, v252, 33
	v_add_u32_e32 v3, 0, v45
	v_mul_lo_u32 v48, v25, s1
	v_mul_u32_u24_e32 v49, 0x90, v0
	v_add_u32_e32 v50, s0, v47
	v_mad_u32_u24 v4, v0, s1, v232
	v_mad_u32_u24 v0, v0, s1, v233
	v_sub_u32_e32 v42, 0x7f, v25
	v_sub_u32_e32 v43, 63, v25
	v_add_u32_e32 v44, 64, v25
	v_add_u32_e32 v46, 0xffffff00, v25
	v_add_u32_e32 v51, v3, v48
	v_add_u32_e32 v52, v2, v49
	v_add_u32_e32 v53, v50, v4
	v_add_u32_e32 v54, v50, v0
	v_readlane_b32 s29, v253, 12
	s_branch .LBB0_542

; DEVI int opaque_tid(int wv) { int ln; asm volatile("v_mbcnt_lo_u32_b32 %0, -1, 0\n\tv_mbcnt_hi_u32_b32 %0, -1, %0" : "=v"(ln)); return wv * 64 + ln; }
; #define PHASED(flag, ph, ...) if ((ph) >= lo && (ph) < hi) { __VA_ARGS__; if (DUPMASK & (flag)) { xcd_barrier(xb, wv); __VA_ARGS__; } if ((ph) + 1 < hi) xcd_barrier(xb, wv); }
; DEVI void xcd_barrier(const XcdBarrier& b, const int wv) {
;     asm volatile("s_waitcnt vmcnt(0)" ::: "memory");
;     __syncthreads();
;     if (opaque_tid(wv) == 0) {
;         unsigned* bar = b.bar;
;         __builtin_amdgcn_s_waitcnt(0);
;         unsigned nloc = b.st[0], nx = b.st[1];
;         if (nloc == 0u) { xcd_barrier_complete(bar, b.x, nloc, nx); b.st[0] = nloc; b.st[1] = nx; }
; __global__ void __launch_bounds__(NTHREADS) mega(Params p) {
;     ...
;         PHASED(4, b + 3, ph_ret_state(wv, p, l, lds_raw); ph_attn(wv, p, l, lds_raw))
.LBB0_669:
	s_setprio 0
	v_readlane_b32 s0, v253, 31
	s_mul_i32 s0, s0, 10
	s_add_i32 s18, s0, 5
	s_cmp_ge_i32 s18, s27
	v_readlane_b32 s50, v253, 28
	s_waitcnt vmcnt(0) lgkmcnt(0)
	s_barrier
	s_cbranch_scc1 .LBB0_723
	s_waitcnt vmcnt(0)
	v_readlane_b32 s0, v250, 57
	s_barrier
	v_mbcnt_lo_u32_b32 v0, -1, 0
	v_mbcnt_hi_u32_b32 v0, -1, v0
	s_nop 0
	v_cmp_eq_u32_e32 vcc, s0, v0
	s_and_saveexec_b64 s[0:1], vcc
	s_cbranch_execz .LBB0_722
	v_readlane_b32 s2, v253, 23
	s_waitcnt vmcnt(0) expcnt(0) lgkmcnt(0)
	s_nop 0
	v_mov_b32_e32 v0, s2
	ds_read_b32 v3, v0
	v_readlane_b32 s2, v253, 24
	s_waitcnt lgkmcnt(0)
	v_cmp_ne_u32_e32 vcc, 0, v3
	v_mov_b32_e32 v0, s2
	ds_read_b32 v2, v0
	s_cbranch_vccnz .LBB0_686
	s_mov_b32 s8, 1
	s_branch .LBB0_674

; #define LAS __attribute__((address_space(3)))
; DEVI int opaque_tid(int wv) { int ln; asm volatile("v_mbcnt_lo_u32_b32 %0, -1, 0\n\tv_mbcnt_hi_u32_b32 %0, -1, %0" : "=v"(ln)); return wv * 64 + ln; }
; DEVI void ph_ret_out(const int wv, const Params& p, int l, unsigned char* lds_raw) {
;     const int tid = opaque_tid(wv), lane = tid & 63, wave = wv, fr = lane & 15, fq = lane >> 4;
;     LAS unsigned char* Kl = (LAS unsigned char*)lds_raw;
;     LAS unsigned char* Ql = Kl + 18432;
;     LAS unsigned char* Vt = Ql + 18432;
;     LAS unsigned char* Rl = Vt + 36864;
;     const bf16_t* Z = (const bf16_t*)(p.ws + OFF_ZG); const bf16_t* RS = (const bf16_t*)(p.ws + OFF_RS); bf16_t* YB = (bf16_t*)(p.ws + OFF_YB);
;     const int nch = l == 0 ? 18 : 16, nitems = 64 * nch;
;     u32x4 pk[2], pq[2], pr[4], pvv[4];
;     ...
;     if ((int)blockIdx.x < nitems) RO_LOAD((int)blockIdx.x);
.Lprio_skip_1:
	v_readlane_b32 s0, v253, 26
	v_readlane_b32 s1, v253, 27
	s_and_b64 s[0:1], s[0:1], exec
	s_cselect_b32 s12, 18, 16
	s_lshl_b32 s13, s12, 6
	v_readlane_b32 s0, v253, 12
	s_movk_i32 s74, 0xc00
	s_cmp_ge_i32 s0, s13
	v_mbcnt_lo_u32_b32 v53, -1, 0
	v_mbcnt_hi_u32_b32 v53, -1, v53
	s_cbranch_scc1 .LBB0_747
	v_cvt_f32_ubyte0_e32 v0, s12
	v_rcp_iflag_f32_e32 v0, v0
	s_sub_i32 s2, 0, s12
	s_mov_b32 s28, s0
	v_readlane_b32 s5, v252, 61
	v_mul_f32_e32 v0, 0x4f7ffffe, v0
	v_cvt_u32_f32_e32 v0, v0
	s_nop 0
	v_readfirstlane_b32 s3, v0
	s_mul_i32 s0, s2, s3
	s_mul_hi_u32 s0, s3, s0
	s_add_i32 s3, s3, s0
	s_mul_hi_u32 s0, s5, s3
	s_mul_i32 s1, s0, s12
	s_sub_i32 s1, s5, s1
	s_add_i32 s4, s0, 1
	s_sub_i32 s5, s1, s12
	s_cmp_ge_u32 s1, s12
	s_cselect_b32 s0, s4, s0
	s_cselect_b32 s1, s5, s1
	s_add_i32 s4, s0, 1
	s_cmp_ge_u32 s1, s12
	s_cselect_b32 s0, s4, s0
	v_readlane_b32 s1, v252, 4
	s_xor_b32 s0, s0, s1
	s_sub_i32 s5, s0, s1
	s_mul_i32 s0, s5, s12
	s_sub_i32 s4, s28, s0
	v_readlane_b32 s0, v253, 26
	s_ashr_i32 s7, s5, 2
	s_add_i32 s6, s4, 2
	v_readlane_b32 s1, v253, 27
	s_and_b64 s[0:1], s[0:1], exec
	s_cselect_b32 s6, s4, s6
	s_cmp_gt_i32 s6, 1
	s_mov_b64 s[0:1], -1
	s_cbranch_scc0 .LBB0_729
	s_lshl_b32 s0, s7, 11
	s_lshl_b32 s1, s6, 7
	s_add_i32 s0, s0, s1
	s_add_i32 s4, s0, 0xffffff00
	s_mov_b64 s[0:1], 0

; DEVI int opaque_tid(int wv) { int ln; asm volatile("v_mbcnt_lo_u32_b32 %0, -1, 0\n\tv_mbcnt_hi_u32_b32 %0, -1, %0" : "=v"(ln)); return wv * 64 + ln; }
; DEVI void xcd_barrier(const XcdBarrier& b, const int wv) {
;     asm volatile("s_waitcnt vmcnt(0)" ::: "memory");
;     __syncthreads();
;     if (opaque_tid(wv) == 0) {
;         unsigned* bar = b.bar;
;         __builtin_amdgcn_s_waitcnt(0);
;         unsigned nloc = b.st[0], nx = b.st[1];
;         if (nloc == 0u) { xcd_barrier_complete(bar, b.x, nloc, nx); b.st[0] = nloc; b.st[1] = nx; }
.LBB0_747:
	s_setprio 0
	v_readlane_b32 s0, v253, 31
	s_mul_i32 s0, s0, 10
	s_add_i32 s18, s0, 6
	s_cmp_ge_i32 s18, s27
	s_waitcnt vmcnt(0) lgkmcnt(0)
	s_barrier
	s_cbranch_scc1 .LBB0_759
	s_waitcnt vmcnt(0)
	v_readlane_b32 s0, v250, 57
	s_barrier
	v_mbcnt_lo_u32_b32 v0, -1, 0
	v_mbcnt_hi_u32_b32 v0, -1, v0
	s_nop 0
	v_cmp_eq_u32_e32 vcc, s0, v0
	s_and_saveexec_b64 s[0:1], vcc
	v_readlane_b32 s50, v253, 28
	s_movk_i32 s55, 0xc00
	s_cbranch_execz .LBB0_801
	v_readlane_b32 s2, v253, 23
	s_waitcnt vmcnt(0) expcnt(0) lgkmcnt(0)
	s_nop 0
	v_mov_b32_e32 v0, s2
	ds_read_b32 v3, v0
	v_readlane_b32 s2, v253, 24
	s_waitcnt lgkmcnt(0)
	v_cmp_ne_u32_e32 vcc, 0, v3
	v_mov_b32_e32 v0, s2
	ds_read_b32 v2, v0
	s_cbranch_vccnz .LBB0_765
	s_mov_b32 s8, 1
	s_branch .LBB0_752
